# w_in phase round 2: 100 of the idle workgroups run plain attention-side w_in units from the mixer queue
# speedup vs baseline: 1.0068x; 1.0068x over previous
.Lwsteal:
	s_cmp_lg_u32 s25, 0
	s_cbranch_scc1 .LBB0_236
	s_add_i32 s5, s24, 0xfffffeaa
	s_cmpk_lt_u32 s5, 0x64
	s_cbranch_scc0 .LBB0_236
	s_add_i32 s5, s5, 0x9c
	s_lshr_b32 s20, s5, 2
	s_and_b32 s21, s5, 3
	s_min_u32 s5, s21, 1
	s_add_i32 s21, s21, s5
	s_add_i32 s5, s21, 5
	s_cmp_lt_u32 s21, 4
	s_cselect_b32 s22, s21, s5
	s_mov_b64 s[2:3], -1

.LBB0_671:
	s_or_b64 exec, exec, s[2:3]
	s_waitcnt vmcnt(0)
	v_readfirstlane_b32 s2, v2
	s_mov_b64 s[8:9], s[72:73]
	s_nop 0
	v_add_u32_e32 v0, s2, v0
	v_add_u32_e32 v2, 0x64, v0
	v_cmp_lt_i32_e32 vcc, 0x11b, v0
	s_nop 1
	v_cndmask_b32_e32 v0, v0, v2, vcc
	v_cmp_gt_i32_e32 vcc, s62, v0
	v_cmp_le_i32_e64 s[2:3], s85, v0
	s_or_b64 s[4:5], vcc, s[2:3]
	s_nor_b64 s[10:11], s[4:5], s[72:73]
	s_and_saveexec_b64 s[4:5], s[10:11]
	s_cbranch_execz .LBB0_686
	s_mov_b32 s10, 0x1000000
	s_branch .LBB0_675

.LBB0_675:
	global_load_dword v2, v1, s[90:91] offset:192 sc1
	s_mov_b64 s[8:9], -1
	s_waitcnt vmcnt(0)
	v_cmp_lt_u32_e32 vcc, 0x11b, v2
	s_cbranch_vccnz .LBB0_674
	s_cmp_lg_u32 s10, 0
	s_sleep 2
	s_cbranch_scc0 .LBB0_673
	global_load_dword v2, v1, s[90:91] offset:192 sc1
	s_waitcnt vmcnt(0)
	v_cmp_gt_u32_e32 vcc, 0x11c, v2
	s_cbranch_vccz .LBB0_674
	s_sleep 2
	global_load_dword v2, v1, s[90:91] offset:192 sc1
	s_waitcnt vmcnt(0)
	v_cmp_gt_u32_e32 vcc, 0x11c, v2
	s_cbranch_vccz .LBB0_674
	s_sleep 2
	global_load_dword v2, v1, s[90:91] offset:192 sc1
	s_waitcnt vmcnt(0)
	v_cmp_gt_u32_e32 vcc, 0x11c, v2
	s_cbranch_vccz .LBB0_674
	s_sleep 2
	global_load_dword v2, v1, s[90:91] offset:192 sc1
	s_waitcnt vmcnt(0)
	v_cmp_gt_u32_e32 vcc, 0x11c, v2
	s_cbranch_vccz .LBB0_674
	s_sleep 2
	global_load_dword v2, v1, s[90:91] offset:192 sc1
	s_waitcnt vmcnt(0)
	v_cmp_gt_u32_e32 vcc, 0x11c, v2
	s_cbranch_vccz .LBB0_674
	s_sleep 2
	global_load_dword v2, v1, s[90:91] offset:192 sc1
	s_waitcnt vmcnt(0)
	v_cmp_gt_u32_e32 vcc, 0x11c, v2
	s_cbranch_vccz .LBB0_674
	s_sleep 2
	global_load_dword v2, v1, s[90:91] offset:192 sc1
	s_waitcnt vmcnt(0)
	v_cmp_gt_u32_e32 vcc, 0x11c, v2
	s_cbranch_vccz .LBB0_674
	s_sleep 2
	s_add_i32 s10, s10, -8
	s_mov_b64 s[8:9], 0
	s_branch .LBB0_674
